# full-grid barriers: waiting workgroups poll the TOP generation word directly (one hop less than their XCD generation word)
# speedup vs baseline: 1.0059x; 1.0050x over previous
; __device__ __forceinline__ unsigned xb_ld(unsigned* p)              { return __hip_atomic_load(p, __ATOMIC_RELAXED, __HIP_MEMORY_SCOPE_AGENT); }
; __device__ __forceinline__ unsigned xb_add(unsigned* p, unsigned v) { return __hip_atomic_fetch_add(p, v, __ATOMIC_RELAXED, __HIP_MEMORY_SCOPE_AGENT); }
; #define XB_SPIN(cond, bar) do { unsigned _sp = 0; while (cond) { __builtin_amdgcn_s_sleep(1); \
;     if ((++_sp & 255u) == 0u) { if (xb_ld(&(bar)[XB_TMO])) break; if (_sp > XB_SPIN_CAP) { atomicAdd(&(bar)[XB_TMO], 1u); break; } } } } while (0)
; __device__ __forceinline__ void xcd_barrier(const XcdBarrier& b) {
;     ...
;         const unsigned old = xb_add(&bar[XB_XSUB(b.x)], 1u);
;         const unsigned gen = old / nloc;
;         if (old + 1u == (gen + 1u) * nloc) {
;             __builtin_amdgcn_fence(__ATOMIC_RELEASE, "agent");
;             asm volatile("s_waitcnt vmcnt(0)" ::: "memory");
;             const unsigned og = xb_add(&bar[XB_TOP], 1u);
;             const unsigned tg = og / nx;
;             if (og + 1u == (tg + 1u) * nx) xb_add(&bar[XB_TOPGEN], 1u);
;             else XB_SPIN(xb_ld(&bar[XB_TOPGEN]) == tg, bar);
;             __builtin_amdgcn_fence(__ATOMIC_ACQUIRE, "agent");
;             xb_add(&bar[XB_XGEN(b.x)], 1u);
;             asm volatile("s_waitcnt vmcnt(0)" ::: "memory");
;         } else {
;             XB_SPIN(xb_ld(&bar[XB_XGEN(b.x)]) == gen, bar);
.LBB0_1178:
	s_or_b64 exec, exec, s[8:9]
	v_cvt_f32_u32_e32 v4, v2
	s_waitcnt vmcnt(0)
	v_readfirstlane_b32 s6, v3
	v_sub_u32_e32 v3, 0, v2
	v_rcp_iflag_f32_e32 v4, v4
	v_add_u32_e32 v5, s6, v1
	v_mul_f32_e32 v4, 0x4f7ffffe, v4
	v_cvt_u32_f32_e32 v4, v4
	v_mul_lo_u32 v1, v3, v4
	v_mul_hi_u32 v1, v4, v1
	v_add_u32_e32 v1, v4, v1
	v_mul_hi_u32 v1, v5, v1
	v_mul_lo_u32 v3, v1, v2
	v_sub_u32_e32 v3, v5, v3
	v_add_u32_e32 v4, 1, v1
	v_cmp_ge_u32_e32 vcc, v3, v2
	s_nop 1
	v_cndmask_b32_e32 v1, v1, v4, vcc
	v_sub_u32_e32 v4, v3, v2
	v_cndmask_b32_e32 v3, v3, v4, vcc
	v_add_u32_e32 v4, 1, v1
	v_cmp_ge_u32_e32 vcc, v3, v2
	v_add_u32_e32 v3, 1, v5
	s_nop 0
	v_cndmask_b32_e32 v1, v1, v4, vcc
	v_mul_lo_u32 v4, v2, v1
	v_add_u32_e32 v2, v4, v2
	v_cmp_ne_u32_e32 vcc, v3, v2
	s_and_saveexec_b64 s[6:7], vcc
	s_xor_b64 s[6:7], exec, s[6:7]
	s_cbranch_execz .LBB0_1192
	s_waitcnt lgkmcnt(0)
	s_add_u32 s12, s34, 0x83500
	s_addc_u32 s13, s35, 0
	v_mov_b32_e32 v0, 0
	global_load_dword v0, v0, s[12:13] sc1
	s_waitcnt vmcnt(0)
	v_cmp_eq_u32_e32 vcc, v0, v1
	s_and_saveexec_b64 s[8:9], vcc
	s_cbranch_execz .LBB0_1191
	s_add_u32 s10, s34, 0x80200
	s_addc_u32 s11, s35, 0
	s_mov_b32 s24, 1
	s_mov_b64 s[14:15], 0
	v_mov_b32_e32 v0, 0
	s_branch .LBB0_1182
